# poolc epilogue hand-written: c_scale vectors and all 8 Y row groups loaded up front instead of a dependent round trip per row group
# speedup vs baseline: 1.0092x; 1.0061x over previous
.LBB0_511:
	v_mov_b32_e32 v99, s18
	v_cmp_lt_u32_e64 s[8:9], s18, v93
	v_cmp_lt_u32_e64 s[14:15], s18, v91
	s_add_i32 s6, s18, 1
	s_add_i32 s7, s18, 2
	s_add_i32 s10, s18, 3
	v_cndmask_b32_e64 v101, 0, v99, s[14:15]
	v_cndmask_b32_e64 v99, 0, v99, s[8:9]
	s_cmp_eq_u32 s18, 0
	v_cndmask_b32_e64 v184, 0, v97, s[8:9]
	v_mad_u64_u32 v[182:183], s[8:9], v101, s55, v[116:117]
	v_mad_u64_u32 v[186:187], s[8:9], v99, s55, v[118:119]
	v_mov_b32_e32 v103, s6
	v_cmp_lt_u32_e64 s[0:1], s6, v91
	v_mov_b32_e32 v105, s7
	v_cmp_lt_u32_e64 s[12:13], s7, v91
	v_mov_b32_e32 v107, s10
	v_cmp_lt_u32_e64 s[4:5], s10, v91
	v_cmp_lt_u32_e32 vcc, s6, v93
	v_cmp_lt_u32_e64 s[6:7], s7, v93
	v_cmp_lt_u32_e64 s[10:11], s10, v93
	s_cselect_b64 s[8:9], -1, 0
	v_cndmask_b32_e64 v109, 0, v95, s[14:15]
	v_cndmask_b32_e64 v192, 0, v103, s[0:1]
	v_cndmask_b32_e64 v193, 0, v105, s[12:13]
	v_cndmask_b32_e64 v196, 0, v107, s[4:5]
	v_cndmask_b32_e32 v103, 0, v103, vcc
	v_cndmask_b32_e64 v105, 0, v105, s[6:7]
	v_cndmask_b32_e64 v107, 0, v107, s[10:11]
	v_cndmask_b32_e64 v185, 0, 1.0, s[8:9]
	v_sub_u32_e32 v183, v183, v101
	v_sub_u32_e32 v187, v187, v99
	v_cndmask_b32_e64 v214, 0, v95, s[0:1]
	v_mad_u64_u32 v[190:191], s[0:1], v192, s55, v[116:117]
	v_mad_u64_u32 v[194:195], s[0:1], v193, s55, v[116:117]
	v_mad_u64_u32 v[198:199], s[0:1], v196, s55, v[116:117]
	v_mad_u64_u32 v[202:203], s[0:1], v103, s55, v[118:119]
	v_mad_u64_u32 v[206:207], s[0:1], v105, s55, v[118:119]
	v_mad_u64_u32 v[210:211], s[0:1], v107, s55, v[118:119]
	v_sub_f32_e32 v226, v109, v185
	v_sub_f32_e32 v228, v184, v185
	global_load_dwordx4 v[182:185], v[182:183], off
	s_nop 0
	global_load_dwordx4 v[186:189], v[186:187], off
	v_sub_u32_e32 v191, v191, v192
	v_sub_u32_e32 v195, v195, v193
	v_sub_u32_e32 v199, v199, v196
	v_sub_u32_e32 v203, v203, v103
	v_sub_u32_e32 v207, v207, v105
	v_sub_u32_e32 v211, v211, v107
	global_load_dwordx4 v[190:193], v[190:191], off
	s_nop 0
	global_load_dwordx4 v[194:197], v[194:195], off
	s_nop 0
	global_load_dwordx4 v[198:201], v[198:199], off
	s_nop 0
	global_load_dwordx4 v[202:205], v[202:203], off
	s_nop 0
	global_load_dwordx4 v[206:209], v[206:207], off
	s_nop 0
	global_load_dwordx4 v[210:213], v[210:211], off
	v_cndmask_b32_e32 v220, 0, v97, vcc
	v_cndmask_b32_e64 v216, 0, v95, s[12:13]
	v_cndmask_b32_e64 v222, 0, v97, s[6:7]
	v_cndmask_b32_e64 v218, 0, v95, s[4:5]
	v_cndmask_b32_e64 v224, 0, v97, s[10:11]
	s_add_i32 s18, s18, 4
	s_cmp_ge_u32 s18, s57
	s_waitcnt vmcnt(0)
	v_and_b32_e32 v231, 0xffff0000, v182
	v_lshlrev_b32_e32 v230, 16, v182
	v_and_b32_e32 v233, 0xffff0000, v183
	v_lshlrev_b32_e32 v232, 16, v183
	v_and_b32_e32 v183, 0xffff0000, v184
	v_lshlrev_b32_e32 v182, 16, v184
	v_and_b32_e32 v235, 0xffff0000, v185
	v_lshlrev_b32_e32 v234, 16, v185
	v_and_b32_e32 v185, 0xffff0000, v186
	v_lshlrev_b32_e32 v184, 16, v186
	v_and_b32_e32 v237, 0xffff0000, v187
	v_lshlrev_b32_e32 v236, 16, v187
	v_and_b32_e32 v187, 0xffff0000, v188
	v_lshlrev_b32_e32 v186, 16, v188
	v_and_b32_e32 v239, 0xffff0000, v189
	v_lshlrev_b32_e32 v238, 16, v189
	v_pk_fma_f32 v[146:147], v[226:227], v[230:231], v[146:147] op_sel_hi:[0,1,1]
	v_and_b32_e32 v189, 0xffff0000, v190
	v_lshlrev_b32_e32 v188, 16, v190
	v_pk_fma_f32 v[144:145], v[226:227], v[232:233], v[144:145] op_sel_hi:[0,1,1]
	v_and_b32_e32 v233, 0xffff0000, v191
	v_lshlrev_b32_e32 v232, 16, v191
	v_pk_fma_f32 v[142:143], v[226:227], v[182:183], v[142:143] op_sel_hi:[0,1,1]
	v_and_b32_e32 v183, 0xffff0000, v192
	v_lshlrev_b32_e32 v182, 16, v192
	v_pk_fma_f32 v[140:141], v[226:227], v[234:235], v[140:141] op_sel_hi:[0,1,1]
	v_and_b32_e32 v227, 0xffff0000, v193
	v_lshlrev_b32_e32 v226, 16, v193
	v_pk_fma_f32 v[126:127], v[228:229], v[184:185], v[126:127] op_sel_hi:[0,1,1]
	v_and_b32_e32 v185, 0xffff0000, v202
	v_lshlrev_b32_e32 v184, 16, v202
	v_pk_fma_f32 v[124:125], v[228:229], v[236:237], v[124:125] op_sel_hi:[0,1,1]
	v_and_b32_e32 v237, 0xffff0000, v203
	v_lshlrev_b32_e32 v236, 16, v203
	v_pk_fma_f32 v[122:123], v[228:229], v[186:187], v[122:123] op_sel_hi:[0,1,1]
	v_and_b32_e32 v187, 0xffff0000, v204
	v_lshlrev_b32_e32 v186, 16, v204
	v_pk_fma_f32 v[120:121], v[228:229], v[238:239], v[120:121] op_sel_hi:[0,1,1]
	v_and_b32_e32 v229, 0xffff0000, v205
	v_lshlrev_b32_e32 v228, 16, v205
	v_and_b32_e32 v231, 0xffff0000, v194
	v_lshlrev_b32_e32 v230, 16, v194
	v_and_b32_e32 v241, 0xffff0000, v198
	v_lshlrev_b32_e32 v240, 16, v198
	v_and_b32_e32 v191, 0xffff0000, v195
	v_lshlrev_b32_e32 v190, 16, v195
	v_and_b32_e32 v195, 0xffff0000, v199
	v_lshlrev_b32_e32 v194, 16, v199
	v_and_b32_e32 v199, 0xffff0000, v196
	v_lshlrev_b32_e32 v198, 16, v196
	v_and_b32_e32 v243, 0xffff0000, v200
	v_lshlrev_b32_e32 v242, 16, v200
	v_and_b32_e32 v193, 0xffff0000, v197
	v_lshlrev_b32_e32 v192, 16, v197
	v_and_b32_e32 v197, 0xffff0000, v201
	v_lshlrev_b32_e32 v196, 16, v201
	v_and_b32_e32 v201, 0xffff0000, v206
	v_lshlrev_b32_e32 v200, 16, v206
	v_and_b32_e32 v235, 0xffff0000, v210
	v_lshlrev_b32_e32 v234, 16, v210
	v_and_b32_e32 v203, 0xffff0000, v207
	v_lshlrev_b32_e32 v202, 16, v207
	v_and_b32_e32 v207, 0xffff0000, v211
	v_lshlrev_b32_e32 v206, 16, v211
	v_and_b32_e32 v211, 0xffff0000, v208
	v_lshlrev_b32_e32 v210, 16, v208
	v_and_b32_e32 v205, 0xffff0000, v209
	v_lshlrev_b32_e32 v204, 16, v209
	v_pk_fma_f32 v[146:147], v[214:215], v[188:189], v[146:147] op_sel_hi:[0,1,1]
	v_pk_fma_f32 v[144:145], v[214:215], v[232:233], v[144:145] op_sel_hi:[0,1,1]
	v_pk_fma_f32 v[142:143], v[214:215], v[182:183], v[142:143] op_sel_hi:[0,1,1]
	v_pk_fma_f32 v[140:141], v[214:215], v[226:227], v[140:141] op_sel_hi:[0,1,1]
	v_pk_fma_f32 v[126:127], v[220:221], v[184:185], v[126:127] op_sel_hi:[0,1,1]
	v_pk_fma_f32 v[124:125], v[220:221], v[236:237], v[124:125] op_sel_hi:[0,1,1]
	v_pk_fma_f32 v[122:123], v[220:221], v[186:187], v[122:123] op_sel_hi:[0,1,1]
	v_pk_fma_f32 v[120:121], v[220:221], v[228:229], v[120:121] op_sel_hi:[0,1,1]
	v_and_b32_e32 v245, 0xffff0000, v212
	v_lshlrev_b32_e32 v244, 16, v212
	v_and_b32_e32 v209, 0xffff0000, v213
	v_lshlrev_b32_e32 v208, 16, v213
	v_pk_fma_f32 v[146:147], v[216:217], v[230:231], v[146:147] op_sel_hi:[0,1,1]
	v_pk_fma_f32 v[144:145], v[216:217], v[190:191], v[144:145] op_sel_hi:[0,1,1]
	v_pk_fma_f32 v[142:143], v[216:217], v[198:199], v[142:143] op_sel_hi:[0,1,1]
	v_pk_fma_f32 v[140:141], v[216:217], v[192:193], v[140:141] op_sel_hi:[0,1,1]
	v_pk_fma_f32 v[126:127], v[222:223], v[200:201], v[126:127] op_sel_hi:[0,1,1]
	v_pk_fma_f32 v[124:125], v[222:223], v[202:203], v[124:125] op_sel_hi:[0,1,1]
	v_pk_fma_f32 v[122:123], v[222:223], v[210:211], v[122:123] op_sel_hi:[0,1,1]
	v_pk_fma_f32 v[120:121], v[222:223], v[204:205], v[120:121] op_sel_hi:[0,1,1]
	v_pk_fma_f32 v[146:147], v[218:219], v[240:241], v[146:147] op_sel_hi:[0,1,1]
	v_pk_fma_f32 v[144:145], v[218:219], v[194:195], v[144:145] op_sel_hi:[0,1,1]
	v_pk_fma_f32 v[142:143], v[218:219], v[242:243], v[142:143] op_sel_hi:[0,1,1]
	v_pk_fma_f32 v[140:141], v[218:219], v[196:197], v[140:141] op_sel_hi:[0,1,1]
	v_pk_fma_f32 v[126:127], v[224:225], v[234:235], v[126:127] op_sel_hi:[0,1,1]
	v_pk_fma_f32 v[124:125], v[224:225], v[206:207], v[124:125] op_sel_hi:[0,1,1]
	v_pk_fma_f32 v[122:123], v[224:225], v[244:245], v[122:123] op_sel_hi:[0,1,1]
	v_pk_fma_f32 v[120:121], v[224:225], v[208:209], v[120:121] op_sel_hi:[0,1,1]
	s_cbranch_scc0 .LBB0_511
	v_cvt_pk_bf16_f32 v119, v140, v141
	v_cvt_pk_bf16_f32 v118, v142, v143
	v_cvt_pk_bf16_f32 v117, v144, v145
	v_cvt_pk_bf16_f32 v116, v146, v147
	v_lshl_or_b32 v64, v64, 7, v162
	ds_write_b128 v64, v[116:119]
	v_cvt_pk_bf16_f32 v119, v120, v121
	v_cvt_pk_bf16_f32 v118, v122, v123
	v_cvt_pk_bf16_f32 v117, v124, v125
	v_cvt_pk_bf16_f32 v116, v126, v127
	s_mov_b32 s4, 64
	s_mov_b64 s[0:1], 0
	s_and_b64 vcc, exec, s[42:43]
	ds_write_b128 v64, v[116:119] offset:4096
	s_cbranch_vccz .LBB0_510
	s_waitcnt vmcnt(0)
	s_waitcnt lgkmcnt(0)
	s_barrier
	ds_read_b128 v[114:117], v175
	ds_read_b128 v[118:121], v176 offset:16384
	ds_read_b128 v[122:125], v176 offset:18432
	ds_read_b128 v[140:143], v176 offset:20480
	s_add_i32 s59, s59, 1
	s_waitcnt lgkmcnt(2)
	v_mfma_f32_16x16x32_bf16 v[32:35], v[114:117], v[118:121], v[32:35]
	ds_read_b128 v[144:147], v175 offset:2048
	s_cmp_lg_u32 s59, 4
	s_waitcnt lgkmcnt(2)
	v_mfma_f32_16x16x32_bf16 v[44:47], v[114:117], v[122:125], v[44:47]
	ds_read_b128 v[182:185], v176 offset:22528
	s_waitcnt lgkmcnt(2)
	v_mfma_f32_16x16x32_bf16 v[40:43], v[114:117], v[140:143], v[40:43]
	ds_read_b128 v[186:189], v176 offset:24576
	s_waitcnt lgkmcnt(1)
	v_mfma_f32_16x16x32_bf16 v[52:55], v[114:117], v[182:185], v[52:55]
	ds_read_b128 v[190:193], v176 offset:26624
	s_waitcnt lgkmcnt(1)
	v_mfma_f32_16x16x32_bf16 v[48:51], v[114:117], v[186:189], v[48:51]
	ds_read_b128 v[194:197], v176 offset:28672
	s_waitcnt lgkmcnt(1)
	v_mfma_f32_16x16x32_bf16 v[56:59], v[114:117], v[190:193], v[56:59]
	ds_read_b128 v[198:201], v176 offset:30720
	s_waitcnt lgkmcnt(1)
	v_mfma_f32_16x16x32_bf16 v[60:63], v[114:117], v[194:197], v[60:63]
	ds_read_b128 v[202:205], v177
	s_waitcnt lgkmcnt(1)
	v_mfma_f32_16x16x32_bf16 v[36:39], v[114:117], v[198:201], v[36:39]
	ds_read_b128 v[114:117], v177 offset:2048
	v_mfma_f32_16x16x32_bf16 v[0:3], v[144:147], v[118:121], v[0:3]
	ds_read_b128 v[118:121], v178 offset:16384
	v_mfma_f32_16x16x32_bf16 v[8:11], v[144:147], v[122:125], v[8:11]
	ds_read_b128 v[122:125], v178 offset:18432
	v_mfma_f32_16x16x32_bf16 v[4:7], v[144:147], v[140:143], v[4:7]
	ds_read_b128 v[140:143], v178 offset:20480
	v_mfma_f32_16x16x32_bf16 v[16:19], v[144:147], v[182:185], v[16:19]
	ds_read_b128 v[182:185], v178 offset:22528
	v_mfma_f32_16x16x32_bf16 v[12:15], v[144:147], v[186:189], v[12:15]
	ds_read_b128 v[186:189], v178 offset:24576
	v_mfma_f32_16x16x32_bf16 v[20:23], v[144:147], v[190:193], v[20:23]
	ds_read_b128 v[190:193], v178 offset:26624
	v_mfma_f32_16x16x32_bf16 v[24:27], v[144:147], v[194:197], v[24:27]
	ds_read_b128 v[194:197], v178 offset:28672
	v_mfma_f32_16x16x32_bf16 v[28:31], v[144:147], v[198:201], v[28:31]
	ds_read_b128 v[144:147], v178 offset:30720
	s_waitcnt lgkmcnt(0)
	s_barrier
	v_mfma_f32_16x16x32_bf16 v[32:35], v[202:205], v[118:121], v[32:35]
	v_mfma_f32_16x16x32_bf16 v[44:47], v[202:205], v[122:125], v[44:47]
	v_mfma_f32_16x16x32_bf16 v[40:43], v[202:205], v[140:143], v[40:43]
	v_mfma_f32_16x16x32_bf16 v[52:55], v[202:205], v[182:185], v[52:55]
	v_mfma_f32_16x16x32_bf16 v[48:51], v[202:205], v[186:189], v[48:51]
	v_mfma_f32_16x16x32_bf16 v[56:59], v[202:205], v[190:193], v[56:59]
	v_mfma_f32_16x16x32_bf16 v[60:63], v[202:205], v[194:197], v[60:63]
	v_mfma_f32_16x16x32_bf16 v[36:39], v[202:205], v[144:147], v[36:39]
	v_mfma_f32_16x16x32_bf16 v[0:3], v[114:117], v[118:121], v[0:3]
	v_mfma_f32_16x16x32_bf16 v[8:11], v[114:117], v[122:125], v[8:11]
	v_mfma_f32_16x16x32_bf16 v[4:7], v[114:117], v[140:143], v[4:7]
	v_mfma_f32_16x16x32_bf16 v[16:19], v[114:117], v[182:185], v[16:19]
	v_mfma_f32_16x16x32_bf16 v[12:15], v[114:117], v[186:189], v[12:15]
	v_mfma_f32_16x16x32_bf16 v[20:23], v[114:117], v[190:193], v[20:23]
	v_mfma_f32_16x16x32_bf16 v[24:27], v[114:117], v[194:197], v[24:27]
	v_mfma_f32_16x16x32_bf16 v[28:31], v[114:117], v[144:147], v[28:31]
	s_cbranch_scc1 .LBB0_509
	s_lshl_b32 s10, s38, 19
	s_lshl_b32 s11, s39, 1
	s_add_i32 s10, s10, s11
	s_add_u32 s4, s36, s10
	s_addc_u32 s5, s37, 0
	s_mov_b32 s6, s4
	s_mov_b32 s7, s5
	s_lshl_b32 s10, s39, 2
	s_add_u32 s8, s40, s10
	s_addc_u32 s9, s41, 0
	v_lshrrev_b32_e32 v64, 4, v129
	v_and_b32_e32 v182, 15, v64
	v_bfe_u32 v183, v64, 4, 2
	v_lshrrev_b32_e32 v184, 6, v64
	v_lshlrev_b32_e32 v93, 5, v182
	v_lshl_add_u32 v187, v184, 5, v183
	v_lshlrev_b32_e32 v188, 4, v182
	v_lshl_add_u32 v91, v187, 12, v188
	v_lshlrev_b32_e32 v187, 13, v184
	v_lshl_add_u32 v188, v183, 3, v182
	v_lshl_add_u32 v189, v183, 11, v187
	v_lshl_add_u32 v95, v188, 2, v189
	v_add_u32_e32 v190, 0x60, v188
	v_and_b32_e32 v190, 0x7f, v190
	v_lshl_add_u32 v97, v190, 2, v189
	v_add_u32_e32 v190, 0x70, v188
	v_and_b32_e32 v190, 0x7f, v190
	v_lshl_add_u32 v99, v190, 2, v189
	v_lshlrev_b32_e32 v190, 3, v182
	v_lshl_add_u32 v192, v183, 9, v187
	v_add_u32_e32 v191, 0, v190
	v_and_b32_e32 v191, 0x7f, v191
	v_lshl_add_u32 v101, v191, 2, v192
	v_add_u32_e32 v191, 8, v190
	v_and_b32_e32 v191, 0x7f, v191
	v_lshl_add_u32 v103, v191, 2, v192
	v_add_u32_e32 v103, 2048, v103
	v_add_u32_e32 v191, 16, v190
	v_and_b32_e32 v191, 0x7f, v191
	v_lshl_add_u32 v105, v191, 2, v192
	v_add_u32_e32 v105, 4096, v105
	v_add_u32_e32 v191, 24, v190
	v_and_b32_e32 v191, 0x7f, v191
	v_lshl_add_u32 v107, v191, 2, v192
	v_add_u32_e32 v107, 6144, v107
	global_load_dwordx4 v[238:241], v93, s[8:9]
	global_load_dwordx4 v[242:245], v93, s[8:9] offset:16
	global_load_dwordx4 v[110:113], v91, s[4:5]
	s_add_u32 s4, s4, 0x4000
	s_addc_u32 s5, s5, 0
	global_load_dwordx4 v[114:117], v91, s[4:5]
	s_add_u32 s4, s4, 0x4000
	s_addc_u32 s5, s5, 0
	global_load_dwordx4 v[118:121], v91, s[4:5]
	s_add_u32 s4, s4, 0x4000
	s_addc_u32 s5, s5, 0
	global_load_dwordx4 v[122:125], v91, s[4:5]
	s_add_u32 s4, s4, 0x4000
	s_addc_u32 s5, s5, 0
	global_load_dwordx4 v[140:143], v91, s[4:5]
	s_add_u32 s4, s4, 0x4000
	s_addc_u32 s5, s5, 0
	global_load_dwordx4 v[144:147], v91, s[4:5]
	s_add_u32 s4, s4, 0x4000
	s_addc_u32 s5, s5, 0
	global_load_dwordx4 v[230:233], v91, s[4:5]
	s_add_u32 s4, s4, 0x4000
	s_addc_u32 s5, s5, 0
	global_load_dwordx4 v[234:237], v91, s[4:5]
	s_add_u32 s4, s4, 0x4000
	s_addc_u32 s5, s5, 0
	ds_write_b32 v95, v32 offset:0
	ds_write_b32 v95, v33 offset:512
	ds_write_b32 v95, v34 offset:1024
	ds_write_b32 v95, v35 offset:1536
	ds_write_b32 v95, v44 offset:64
	ds_write_b32 v95, v45 offset:576
	ds_write_b32 v95, v46 offset:1088
	ds_write_b32 v95, v47 offset:1600
	ds_write_b32 v95, v40 offset:128
	ds_write_b32 v95, v41 offset:640
	ds_write_b32 v95, v42 offset:1152
	ds_write_b32 v95, v43 offset:1664
	ds_write_b32 v95, v52 offset:192
	ds_write_b32 v95, v53 offset:704
	ds_write_b32 v95, v54 offset:1216
	ds_write_b32 v95, v55 offset:1728
	ds_write_b32 v95, v48 offset:256
	ds_write_b32 v95, v49 offset:768
	ds_write_b32 v95, v50 offset:1280
	ds_write_b32 v95, v51 offset:1792
	ds_write_b32 v95, v56 offset:320
	ds_write_b32 v95, v57 offset:832
	ds_write_b32 v95, v58 offset:1344
	ds_write_b32 v95, v59 offset:1856
	ds_write_b32 v97, v60 offset:0
	ds_write_b32 v97, v61 offset:512
	ds_write_b32 v97, v62 offset:1024
	ds_write_b32 v97, v63 offset:1536
	ds_write_b32 v99, v36 offset:0
	ds_write_b32 v99, v37 offset:512
	ds_write_b32 v99, v38 offset:1024
	ds_write_b32 v99, v39 offset:1536
	s_waitcnt lgkmcnt(0)
	ds_read_b128 v[32:35], v101
	ds_read_b128 v[44:47], v101 offset:16
	ds_read_b128 v[40:43], v103
	ds_read_b128 v[52:55], v103 offset:16
	ds_read_b128 v[48:51], v105
	ds_read_b128 v[56:59], v105 offset:16
	ds_read_b128 v[60:63], v107
	ds_read_b128 v[36:39], v107 offset:16
	s_waitcnt vmcnt(7) lgkmcnt(6)
	v_mul_f32_e32 v32, v32, v238
	v_mul_f32_e32 v33, v33, v239
	v_mul_f32_e32 v34, v34, v240
	v_mul_f32_e32 v35, v35, v241
	v_mul_f32_e32 v44, v44, v242
	v_mul_f32_e32 v45, v45, v243
	v_mul_f32_e32 v46, v46, v244
	v_mul_f32_e32 v47, v47, v245
	v_lshlrev_b32_e32 v248, 16, v110
	v_lshlrev_b32_e32 v249, 16, v111
	v_lshlrev_b32_e32 v250, 16, v112
	v_lshlrev_b32_e32 v251, 16, v113
	v_and_b32_e32 v110, 0xffff0000, v110
	v_and_b32_e32 v111, 0xffff0000, v111
	v_and_b32_e32 v112, 0xffff0000, v112
	v_and_b32_e32 v113, 0xffff0000, v113
	v_mul_f32_e32 v32, v32, v248
	v_mul_f32_e32 v33, v33, v110
	v_mul_f32_e32 v34, v34, v249
	v_mul_f32_e32 v35, v35, v111
	v_mul_f32_e32 v44, v44, v250
	v_mul_f32_e32 v45, v45, v112
	v_mul_f32_e32 v46, v46, v251
	v_mul_f32_e32 v47, v47, v113
	v_cvt_pk_bf16_f32 v32, v32, v33
	v_cvt_pk_bf16_f32 v33, v34, v35
	v_cvt_pk_bf16_f32 v34, v44, v45
	v_cvt_pk_bf16_f32 v35, v46, v47
	global_store_dwordx4 v91, v[32:35], s[6:7]
	s_add_u32 s6, s6, 0x4000
	s_addc_u32 s7, s7, 0
	s_waitcnt vmcnt(7) lgkmcnt(4)
	v_mul_f32_e32 v40, v40, v238
	v_mul_f32_e32 v41, v41, v239
	v_mul_f32_e32 v42, v42, v240
	v_mul_f32_e32 v43, v43, v241
	v_mul_f32_e32 v52, v52, v242
	v_mul_f32_e32 v53, v53, v243
	v_mul_f32_e32 v54, v54, v244
	v_mul_f32_e32 v55, v55, v245
	v_lshlrev_b32_e32 v248, 16, v114
	v_lshlrev_b32_e32 v249, 16, v115
	v_lshlrev_b32_e32 v250, 16, v116
	v_lshlrev_b32_e32 v251, 16, v117
	v_and_b32_e32 v114, 0xffff0000, v114
	v_and_b32_e32 v115, 0xffff0000, v115
	v_and_b32_e32 v116, 0xffff0000, v116
	v_and_b32_e32 v117, 0xffff0000, v117
	v_mul_f32_e32 v40, v40, v248
	v_mul_f32_e32 v41, v41, v114
	v_mul_f32_e32 v42, v42, v249
	v_mul_f32_e32 v43, v43, v115
	v_mul_f32_e32 v52, v52, v250
	v_mul_f32_e32 v53, v53, v116
	v_mul_f32_e32 v54, v54, v251
	v_mul_f32_e32 v55, v55, v117
	v_cvt_pk_bf16_f32 v40, v40, v41
	v_cvt_pk_bf16_f32 v41, v42, v43
	v_cvt_pk_bf16_f32 v42, v52, v53
	v_cvt_pk_bf16_f32 v43, v54, v55
	global_store_dwordx4 v91, v[40:43], s[6:7]
	s_add_u32 s6, s6, 0x4000
	s_addc_u32 s7, s7, 0
	s_waitcnt vmcnt(7) lgkmcnt(2)
	v_mul_f32_e32 v48, v48, v238
	v_mul_f32_e32 v49, v49, v239
	v_mul_f32_e32 v50, v50, v240
	v_mul_f32_e32 v51, v51, v241
	v_mul_f32_e32 v56, v56, v242
	v_mul_f32_e32 v57, v57, v243
	v_mul_f32_e32 v58, v58, v244
	v_mul_f32_e32 v59, v59, v245
	v_lshlrev_b32_e32 v248, 16, v118
	v_lshlrev_b32_e32 v249, 16, v119
	v_lshlrev_b32_e32 v250, 16, v120
	v_lshlrev_b32_e32 v251, 16, v121
	v_and_b32_e32 v118, 0xffff0000, v118
	v_and_b32_e32 v119, 0xffff0000, v119
	v_and_b32_e32 v120, 0xffff0000, v120
	v_and_b32_e32 v121, 0xffff0000, v121
	v_mul_f32_e32 v48, v48, v248
	v_mul_f32_e32 v49, v49, v118
	v_mul_f32_e32 v50, v50, v249
	v_mul_f32_e32 v51, v51, v119
	v_mul_f32_e32 v56, v56, v250
	v_mul_f32_e32 v57, v57, v120
	v_mul_f32_e32 v58, v58, v251
	v_mul_f32_e32 v59, v59, v121
	v_cvt_pk_bf16_f32 v48, v48, v49
	v_cvt_pk_bf16_f32 v49, v50, v51
	v_cvt_pk_bf16_f32 v50, v56, v57
	v_cvt_pk_bf16_f32 v51, v58, v59
	global_store_dwordx4 v91, v[48:51], s[6:7]
	s_add_u32 s6, s6, 0x4000
	s_addc_u32 s7, s7, 0
	s_waitcnt vmcnt(7) lgkmcnt(0)
	v_mul_f32_e32 v60, v60, v238
	v_mul_f32_e32 v61, v61, v239
	v_mul_f32_e32 v62, v62, v240
	v_mul_f32_e32 v63, v63, v241
	v_mul_f32_e32 v36, v36, v242
	v_mul_f32_e32 v37, v37, v243
	v_mul_f32_e32 v38, v38, v244
	v_mul_f32_e32 v39, v39, v245
	v_lshlrev_b32_e32 v248, 16, v122
	v_lshlrev_b32_e32 v249, 16, v123
	v_lshlrev_b32_e32 v250, 16, v124
	v_lshlrev_b32_e32 v251, 16, v125
	v_and_b32_e32 v122, 0xffff0000, v122
	v_and_b32_e32 v123, 0xffff0000, v123
	v_and_b32_e32 v124, 0xffff0000, v124
	v_and_b32_e32 v125, 0xffff0000, v125
	v_mul_f32_e32 v60, v60, v248
	v_mul_f32_e32 v61, v61, v122
	v_mul_f32_e32 v62, v62, v249
	v_mul_f32_e32 v63, v63, v123
	v_mul_f32_e32 v36, v36, v250
	v_mul_f32_e32 v37, v37, v124
	v_mul_f32_e32 v38, v38, v251
	v_mul_f32_e32 v39, v39, v125
	v_cvt_pk_bf16_f32 v60, v60, v61
	v_cvt_pk_bf16_f32 v61, v62, v63
	v_cvt_pk_bf16_f32 v62, v36, v37
	v_cvt_pk_bf16_f32 v63, v38, v39
	global_store_dwordx4 v91, v[60:63], s[6:7]
	s_add_u32 s6, s6, 0x4000
	s_addc_u32 s7, s7, 0
	ds_write_b32 v95, v0 offset:0
	ds_write_b32 v95, v1 offset:512
	ds_write_b32 v95, v2 offset:1024
	ds_write_b32 v95, v3 offset:1536
	ds_write_b32 v95, v8 offset:64
	ds_write_b32 v95, v9 offset:576
	ds_write_b32 v95, v10 offset:1088
	ds_write_b32 v95, v11 offset:1600
	ds_write_b32 v95, v4 offset:128
	ds_write_b32 v95, v5 offset:640
	ds_write_b32 v95, v6 offset:1152
	ds_write_b32 v95, v7 offset:1664
	ds_write_b32 v95, v16 offset:192
	ds_write_b32 v95, v17 offset:704
	ds_write_b32 v95, v18 offset:1216
	ds_write_b32 v95, v19 offset:1728
	ds_write_b32 v95, v12 offset:256
	ds_write_b32 v95, v13 offset:768
	ds_write_b32 v95, v14 offset:1280
	ds_write_b32 v95, v15 offset:1792
	ds_write_b32 v95, v20 offset:320
	ds_write_b32 v95, v21 offset:832
	ds_write_b32 v95, v22 offset:1344
	ds_write_b32 v95, v23 offset:1856
	ds_write_b32 v97, v24 offset:0
	ds_write_b32 v97, v25 offset:512
	ds_write_b32 v97, v26 offset:1024
	ds_write_b32 v97, v27 offset:1536
	ds_write_b32 v99, v28 offset:0
	ds_write_b32 v99, v29 offset:512
	ds_write_b32 v99, v30 offset:1024
	ds_write_b32 v99, v31 offset:1536
	s_waitcnt lgkmcnt(0)
	ds_read_b128 v[0:3], v101
	ds_read_b128 v[8:11], v101 offset:16
	ds_read_b128 v[4:7], v103
	ds_read_b128 v[16:19], v103 offset:16
	ds_read_b128 v[12:15], v105
	ds_read_b128 v[20:23], v105 offset:16
	ds_read_b128 v[24:27], v107
	ds_read_b128 v[28:31], v107 offset:16
	s_waitcnt vmcnt(7) lgkmcnt(6)
	v_mul_f32_e32 v0, v0, v238
	v_mul_f32_e32 v1, v1, v239
	v_mul_f32_e32 v2, v2, v240
	v_mul_f32_e32 v3, v3, v241
	v_mul_f32_e32 v8, v8, v242
	v_mul_f32_e32 v9, v9, v243
	v_mul_f32_e32 v10, v10, v244
	v_mul_f32_e32 v11, v11, v245
	v_lshlrev_b32_e32 v248, 16, v140
	v_lshlrev_b32_e32 v249, 16, v141
	v_lshlrev_b32_e32 v250, 16, v142
	v_lshlrev_b32_e32 v251, 16, v143
	v_and_b32_e32 v140, 0xffff0000, v140
	v_and_b32_e32 v141, 0xffff0000, v141
	v_and_b32_e32 v142, 0xffff0000, v142
	v_and_b32_e32 v143, 0xffff0000, v143
	v_mul_f32_e32 v0, v0, v248
	v_mul_f32_e32 v1, v1, v140
	v_mul_f32_e32 v2, v2, v249
	v_mul_f32_e32 v3, v3, v141
	v_mul_f32_e32 v8, v8, v250
	v_mul_f32_e32 v9, v9, v142
	v_mul_f32_e32 v10, v10, v251
	v_mul_f32_e32 v11, v11, v143
	v_cvt_pk_bf16_f32 v0, v0, v1
	v_cvt_pk_bf16_f32 v1, v2, v3
	v_cvt_pk_bf16_f32 v2, v8, v9
	v_cvt_pk_bf16_f32 v3, v10, v11
	global_store_dwordx4 v91, v[0:3], s[6:7]
	s_add_u32 s6, s6, 0x4000
	s_addc_u32 s7, s7, 0
	s_waitcnt vmcnt(7) lgkmcnt(4)
	v_mul_f32_e32 v4, v4, v238
	v_mul_f32_e32 v5, v5, v239
	v_mul_f32_e32 v6, v6, v240
	v_mul_f32_e32 v7, v7, v241
	v_mul_f32_e32 v16, v16, v242
	v_mul_f32_e32 v17, v17, v243
	v_mul_f32_e32 v18, v18, v244
	v_mul_f32_e32 v19, v19, v245
	v_lshlrev_b32_e32 v248, 16, v144
	v_lshlrev_b32_e32 v249, 16, v145
	v_lshlrev_b32_e32 v250, 16, v146
	v_lshlrev_b32_e32 v251, 16, v147
	v_and_b32_e32 v144, 0xffff0000, v144
	v_and_b32_e32 v145, 0xffff0000, v145
	v_and_b32_e32 v146, 0xffff0000, v146
	v_and_b32_e32 v147, 0xffff0000, v147
	v_mul_f32_e32 v4, v4, v248
	v_mul_f32_e32 v5, v5, v144
	v_mul_f32_e32 v6, v6, v249
	v_mul_f32_e32 v7, v7, v145
	v_mul_f32_e32 v16, v16, v250
	v_mul_f32_e32 v17, v17, v146
	v_mul_f32_e32 v18, v18, v251
	v_mul_f32_e32 v19, v19, v147
	v_cvt_pk_bf16_f32 v4, v4, v5
	v_cvt_pk_bf16_f32 v5, v6, v7
	v_cvt_pk_bf16_f32 v6, v16, v17
	v_cvt_pk_bf16_f32 v7, v18, v19
	global_store_dwordx4 v91, v[4:7], s[6:7]
	s_add_u32 s6, s6, 0x4000
	s_addc_u32 s7, s7, 0
	s_waitcnt vmcnt(7) lgkmcnt(2)
	v_mul_f32_e32 v12, v12, v238
	v_mul_f32_e32 v13, v13, v239
	v_mul_f32_e32 v14, v14, v240
	v_mul_f32_e32 v15, v15, v241
	v_mul_f32_e32 v20, v20, v242
	v_mul_f32_e32 v21, v21, v243
	v_mul_f32_e32 v22, v22, v244
	v_mul_f32_e32 v23, v23, v245
	v_lshlrev_b32_e32 v248, 16, v230
	v_lshlrev_b32_e32 v249, 16, v231
	v_lshlrev_b32_e32 v250, 16, v232
	v_lshlrev_b32_e32 v251, 16, v233
	v_and_b32_e32 v230, 0xffff0000, v230
	v_and_b32_e32 v231, 0xffff0000, v231
	v_and_b32_e32 v232, 0xffff0000, v232
	v_and_b32_e32 v233, 0xffff0000, v233
	v_mul_f32_e32 v12, v12, v248
	v_mul_f32_e32 v13, v13, v230
	v_mul_f32_e32 v14, v14, v249
	v_mul_f32_e32 v15, v15, v231
	v_mul_f32_e32 v20, v20, v250
	v_mul_f32_e32 v21, v21, v232
	v_mul_f32_e32 v22, v22, v251
	v_mul_f32_e32 v23, v23, v233
	v_cvt_pk_bf16_f32 v12, v12, v13
	v_cvt_pk_bf16_f32 v13, v14, v15
	v_cvt_pk_bf16_f32 v14, v20, v21
	v_cvt_pk_bf16_f32 v15, v22, v23
	global_store_dwordx4 v91, v[12:15], s[6:7]
	s_add_u32 s6, s6, 0x4000
	s_addc_u32 s7, s7, 0
	s_waitcnt vmcnt(7) lgkmcnt(0)
	v_mul_f32_e32 v24, v24, v238
	v_mul_f32_e32 v25, v25, v239
	v_mul_f32_e32 v26, v26, v240
	v_mul_f32_e32 v27, v27, v241
	v_mul_f32_e32 v28, v28, v242
	v_mul_f32_e32 v29, v29, v243
	v_mul_f32_e32 v30, v30, v244
	v_mul_f32_e32 v31, v31, v245
	v_lshlrev_b32_e32 v248, 16, v234
	v_lshlrev_b32_e32 v249, 16, v235
	v_lshlrev_b32_e32 v250, 16, v236
	v_lshlrev_b32_e32 v251, 16, v237
	v_and_b32_e32 v234, 0xffff0000, v234
	v_and_b32_e32 v235, 0xffff0000, v235
	v_and_b32_e32 v236, 0xffff0000, v236
	v_and_b32_e32 v237, 0xffff0000, v237
	v_mul_f32_e32 v24, v24, v248
	v_mul_f32_e32 v25, v25, v234
	v_mul_f32_e32 v26, v26, v249
	v_mul_f32_e32 v27, v27, v235
	v_mul_f32_e32 v28, v28, v250
	v_mul_f32_e32 v29, v29, v236
	v_mul_f32_e32 v30, v30, v251
	v_mul_f32_e32 v31, v31, v237
	v_cvt_pk_bf16_f32 v24, v24, v25
	v_cvt_pk_bf16_f32 v25, v26, v27
	v_cvt_pk_bf16_f32 v26, v28, v29
	v_cvt_pk_bf16_f32 v27, v30, v31
	global_store_dwordx4 v91, v[24:27], s[6:7]
	s_add_u32 s6, s6, 0x4000
	s_addc_u32 s7, s7, 0
	s_branch .LBB0_502
